# v91 + kconst: 0x18000/0x1c000 SALU constants folded into the phase-4 m0 adds in the P1/S4 K-loops (-2 SALU per body)
# speedup vs baseline: 1.0032x; 1.0032x over previous
.LBB0_367:
	s_ashr_i32 s55, s54, 31
	s_lshl_b64 s[2:3], s[54:55], 19
	s_add_u32 s58, s4, s2
	s_addc_u32 s59, s5, s3
	s_and_b64 s[2:3], s[56:57], exec
	s_cselect_b32 s2, s59, s7
	s_cselect_b32 s3, s58, s6
	s_ashr_i32 s53, s52, 31
	s_lshl_b64 s[10:11], s[52:53], 19
	s_add_u32 s60, s15, s10
	s_addc_u32 s61, s78, s11
	s_and_b64 s[10:11], s[56:57], exec
	s_cselect_b32 s12, s61, s9
	s_cselect_b32 s13, s60, s8
	s_add_u32 s6, s6, 0x40080
	s_addc_u32 s7, s7, 0
	s_add_u32 s24, s8, 0x100
	s_addc_u32 s25, s9, 0
	s_mov_b32 s26, -2
	v_add_u32_e32 v254, 0x18000, v173
	v_add_u32_e32 v255, 0x1c000, v173
	ds_read_b128 v[114:117], v197
	ds_read_b128 v[134:137], v197 offset:1024
	ds_read_b128 v[138:141], v197 offset:2048
	ds_read_b128 v[142:145], v197 offset:3072
	ds_read_b128 v[146:149], v198
	ds_read_b128 v[150:153], v198 offset:1024
	ds_read_b128 v[154:157], v198 offset:2048
	ds_read_b128 v[158:161], v198 offset:3072
	s_add_u32 s0, s6, 0xfffc0080
	s_addc_u32 s8, s7, -1
	s_cmp_eq_u32 s26, 12
	s_cselect_b32 s11, s2, s8
	s_cselect_b32 s10, s3, s0
	s_cselect_b32 s9, s12, s25
	s_cselect_b32 s8, s13, s24
	s_add_i32 m0, s31, 0xc000
	ds_read_b128 v[184:187], v199
	ds_read_b128 v[188:191], v199 offset:1024
	ds_read_b128 v[206:209], v199 offset:2048
	ds_read_b128 v[210:213], v199 offset:3072
	ds_read_b128 v[214:217], v199 offset:4096
	ds_read_b128 v[218:221], v199 offset:5120
	ds_read_b128 v[222:225], v199 offset:6144
	global_load_lds_dwordx4 v180, s[6:7]
	s_add_i32 m0, s31, 0xe000
	ds_read_b128 v[226:229], v199 offset:7168
	global_load_lds_dwordx4 v182, s[6:7]
	s_waitcnt vmcnt(8)
	s_waitcnt lgkmcnt(0)
	s_barrier
	s_setprio 1
	v_mfma_f32_16x16x32_bf16 v[130:133], v[114:117], v[184:187], 0
	v_mfma_f32_16x16x32_bf16 v[126:129], v[138:141], v[184:187], 0
	v_mfma_f32_16x16x32_bf16 v[110:113], v[114:117], v[206:209], 0
	v_mfma_f32_16x16x32_bf16 v[106:109], v[138:141], v[206:209], 0
	v_mfma_f32_16x16x32_bf16 v[94:97], v[114:117], v[214:217], 0
	v_mfma_f32_16x16x32_bf16 v[90:93], v[138:141], v[214:217], 0
	v_mfma_f32_16x16x32_bf16 v[78:81], v[114:117], v[222:225], 0
	v_mfma_f32_16x16x32_bf16 v[74:77], v[138:141], v[222:225], 0
	v_mfma_f32_16x16x32_bf16 v[130:133], v[134:137], v[188:191], v[130:133]
	v_mfma_f32_16x16x32_bf16 v[126:129], v[142:145], v[188:191], v[126:129]
	v_mfma_f32_16x16x32_bf16 v[110:113], v[134:137], v[210:213], v[110:113]
	v_mfma_f32_16x16x32_bf16 v[106:109], v[142:145], v[210:213], v[106:109]
	v_mfma_f32_16x16x32_bf16 v[94:97], v[134:137], v[218:221], v[94:97]
	v_mfma_f32_16x16x32_bf16 v[90:93], v[142:145], v[218:221], v[90:93]
	v_mfma_f32_16x16x32_bf16 v[78:81], v[134:137], v[226:229], v[78:81]
	v_mfma_f32_16x16x32_bf16 v[74:77], v[142:145], v[226:229], v[74:77]
	v_mfma_f32_16x16x32_bf16 v[122:125], v[146:149], v[184:187], 0
	v_mfma_f32_16x16x32_bf16 v[118:121], v[154:157], v[184:187], 0
	v_mfma_f32_16x16x32_bf16 v[102:105], v[146:149], v[206:209], 0
	v_mfma_f32_16x16x32_bf16 v[98:101], v[154:157], v[206:209], 0
	v_mfma_f32_16x16x32_bf16 v[86:89], v[146:149], v[214:217], 0
	v_mfma_f32_16x16x32_bf16 v[82:85], v[154:157], v[214:217], 0
	v_mfma_f32_16x16x32_bf16 v[70:73], v[146:149], v[222:225], 0
	v_mfma_f32_16x16x32_bf16 v[66:69], v[154:157], v[222:225], 0
	v_mfma_f32_16x16x32_bf16 v[122:125], v[150:153], v[188:191], v[122:125]
	v_mfma_f32_16x16x32_bf16 v[118:121], v[158:161], v[188:191], v[118:121]
	v_mfma_f32_16x16x32_bf16 v[102:105], v[150:153], v[210:213], v[102:105]
	v_mfma_f32_16x16x32_bf16 v[98:101], v[158:161], v[210:213], v[98:101]
	v_mfma_f32_16x16x32_bf16 v[86:89], v[150:153], v[218:221], v[86:89]
	v_mfma_f32_16x16x32_bf16 v[82:85], v[158:161], v[218:221], v[82:85]
	v_mfma_f32_16x16x32_bf16 v[70:73], v[150:153], v[226:229], v[70:73]
	v_mfma_f32_16x16x32_bf16 v[66:69], v[158:161], v[226:229], v[66:69]
	s_setprio 0
	s_barrier
	s_add_i32 s0, s89, s79
	s_mov_b32 m0, s0
	ds_read_b128 v[184:187], v199 offset:16384
	ds_read_b128 v[188:191], v199 offset:17408
	ds_read_b128 v[206:209], v199 offset:18432
	ds_read_b128 v[210:213], v199 offset:19456
	global_load_lds_dwordx4 v164, s[8:9]
	s_add_i32 m0, s0, 0x2000
	s_add_u32 s62, s8, 0x40000
	s_addc_u32 s63, s9, 0
	s_add_i32 s0, s90, s79
	global_load_lds_dwordx4 v168, s[8:9]
	s_mov_b32 m0, s0
	ds_read_b128 v[214:217], v199 offset:20480
	global_load_lds_dwordx4 v164, s[62:63]
	s_add_i32 m0, s0, 0x2000
	ds_read_b128 v[218:221], v199 offset:21504
	global_load_lds_dwordx4 v168, s[62:63]
	s_mov_b32 m0, s31
	ds_read_b128 v[222:225], v199 offset:22528
	global_load_lds_dwordx4 v162, s[10:11]
	s_mov_b32 m0, s80
	ds_read_b128 v[226:229], v199 offset:23552
	global_load_lds_dwordx4 v166, s[10:11]
	s_waitcnt vmcnt(8)
	s_waitcnt lgkmcnt(0)
	s_barrier
	s_setprio 1
	v_mfma_f32_16x16x32_bf16 v[62:65], v[114:117], v[184:187], 0
	v_mfma_f32_16x16x32_bf16 v[58:61], v[138:141], v[184:187], 0
	v_mfma_f32_16x16x32_bf16 v[46:49], v[114:117], v[206:209], 0
	v_mfma_f32_16x16x32_bf16 v[42:45], v[138:141], v[206:209], 0
	v_mfma_f32_16x16x32_bf16 v[30:33], v[114:117], v[214:217], 0
	v_mfma_f32_16x16x32_bf16 v[26:29], v[138:141], v[214:217], 0
	v_mfma_f32_16x16x32_bf16 v[14:17], v[114:117], v[222:225], 0
	v_mfma_f32_16x16x32_bf16 v[10:13], v[138:141], v[222:225], 0
	v_mfma_f32_16x16x32_bf16 v[62:65], v[134:137], v[188:191], v[62:65]
	v_mfma_f32_16x16x32_bf16 v[58:61], v[142:145], v[188:191], v[58:61]
	v_mfma_f32_16x16x32_bf16 v[46:49], v[134:137], v[210:213], v[46:49]
	v_mfma_f32_16x16x32_bf16 v[42:45], v[142:145], v[210:213], v[42:45]
	v_mfma_f32_16x16x32_bf16 v[30:33], v[134:137], v[218:221], v[30:33]
	v_mfma_f32_16x16x32_bf16 v[26:29], v[142:145], v[218:221], v[26:29]
	v_mfma_f32_16x16x32_bf16 v[14:17], v[134:137], v[226:229], v[14:17]
	v_mfma_f32_16x16x32_bf16 v[10:13], v[142:145], v[226:229], v[10:13]
	v_mfma_f32_16x16x32_bf16 v[54:57], v[146:149], v[184:187], 0
	v_mfma_f32_16x16x32_bf16 v[50:53], v[154:157], v[184:187], 0
	v_mfma_f32_16x16x32_bf16 v[38:41], v[146:149], v[206:209], 0
	v_mfma_f32_16x16x32_bf16 v[34:37], v[154:157], v[206:209], 0
	v_mfma_f32_16x16x32_bf16 v[22:25], v[146:149], v[214:217], 0
	v_mfma_f32_16x16x32_bf16 v[18:21], v[154:157], v[214:217], 0
	v_mfma_f32_16x16x32_bf16 v[6:9], v[146:149], v[222:225], 0
	v_mfma_f32_16x16x32_bf16 v[2:5], v[154:157], v[222:225], 0
	v_mfma_f32_16x16x32_bf16 v[54:57], v[150:153], v[188:191], v[54:57]
	v_mfma_f32_16x16x32_bf16 v[50:53], v[158:161], v[188:191], v[50:53]
	v_mfma_f32_16x16x32_bf16 v[38:41], v[150:153], v[210:213], v[38:41]
	v_mfma_f32_16x16x32_bf16 v[34:37], v[158:161], v[210:213], v[34:37]
	v_mfma_f32_16x16x32_bf16 v[22:25], v[150:153], v[218:221], v[22:25]
	v_mfma_f32_16x16x32_bf16 v[18:21], v[158:161], v[218:221], v[18:21]
	v_mfma_f32_16x16x32_bf16 v[6:9], v[150:153], v[226:229], v[6:9]
	v_mfma_f32_16x16x32_bf16 v[2:5], v[158:161], v[226:229], v[2:5]
	s_setprio 0
	s_barrier
	ds_read_b128 v[114:117], v254
	ds_read_b128 v[134:137], v254 offset:1024
	ds_read_b128 v[138:141], v254 offset:2048
	ds_read_b128 v[142:145], v254 offset:3072
	ds_read_b128 v[146:149], v255
	ds_read_b128 v[150:153], v255 offset:1024
	ds_read_b128 v[154:157], v255 offset:2048
	ds_read_b128 v[158:161], v255 offset:3072
	s_add_u32 s10, s10, 0x40000
	s_addc_u32 s11, s11, 0
	s_mov_b32 m0, s81
	ds_read_b128 v[184:187], v199 offset:32768
	ds_read_b128 v[188:191], v199 offset:33792
	ds_read_b128 v[206:209], v199 offset:34816
	ds_read_b128 v[210:213], v199 offset:35840
	ds_read_b128 v[214:217], v199 offset:36864
	ds_read_b128 v[218:221], v199 offset:37888
	ds_read_b128 v[222:225], v199 offset:38912
	global_load_lds_dwordx4 v162, s[10:11]
	s_mov_b32 m0, s82
	ds_read_b128 v[226:229], v199 offset:39936
	global_load_lds_dwordx4 v166, s[10:11]
	s_waitcnt vmcnt(8)
	s_waitcnt lgkmcnt(0)
	s_barrier
	s_setprio 1
	v_mfma_f32_16x16x32_bf16 v[130:133], v[114:117], v[184:187], v[130:133]
	v_mfma_f32_16x16x32_bf16 v[126:129], v[138:141], v[184:187], v[126:129]
	v_mfma_f32_16x16x32_bf16 v[110:113], v[114:117], v[206:209], v[110:113]
	v_mfma_f32_16x16x32_bf16 v[106:109], v[138:141], v[206:209], v[106:109]
	v_mfma_f32_16x16x32_bf16 v[94:97], v[114:117], v[214:217], v[94:97]
	v_mfma_f32_16x16x32_bf16 v[90:93], v[138:141], v[214:217], v[90:93]
	v_mfma_f32_16x16x32_bf16 v[78:81], v[114:117], v[222:225], v[78:81]
	v_mfma_f32_16x16x32_bf16 v[74:77], v[138:141], v[222:225], v[74:77]
	v_mfma_f32_16x16x32_bf16 v[130:133], v[134:137], v[188:191], v[130:133]
	v_mfma_f32_16x16x32_bf16 v[126:129], v[142:145], v[188:191], v[126:129]
	v_mfma_f32_16x16x32_bf16 v[110:113], v[134:137], v[210:213], v[110:113]
	v_mfma_f32_16x16x32_bf16 v[106:109], v[142:145], v[210:213], v[106:109]
	v_mfma_f32_16x16x32_bf16 v[94:97], v[134:137], v[218:221], v[94:97]
	v_mfma_f32_16x16x32_bf16 v[90:93], v[142:145], v[218:221], v[90:93]
	v_mfma_f32_16x16x32_bf16 v[78:81], v[134:137], v[226:229], v[78:81]
	v_mfma_f32_16x16x32_bf16 v[74:77], v[142:145], v[226:229], v[74:77]
	v_mfma_f32_16x16x32_bf16 v[122:125], v[146:149], v[184:187], v[122:125]
	v_mfma_f32_16x16x32_bf16 v[118:121], v[154:157], v[184:187], v[118:121]
	v_mfma_f32_16x16x32_bf16 v[102:105], v[146:149], v[206:209], v[102:105]
	v_mfma_f32_16x16x32_bf16 v[98:101], v[154:157], v[206:209], v[98:101]
	v_mfma_f32_16x16x32_bf16 v[86:89], v[146:149], v[214:217], v[86:89]
	v_mfma_f32_16x16x32_bf16 v[82:85], v[154:157], v[214:217], v[82:85]
	v_mfma_f32_16x16x32_bf16 v[70:73], v[146:149], v[222:225], v[70:73]
	v_mfma_f32_16x16x32_bf16 v[66:69], v[154:157], v[222:225], v[66:69]
	v_mfma_f32_16x16x32_bf16 v[122:125], v[150:153], v[188:191], v[122:125]
	v_mfma_f32_16x16x32_bf16 v[118:121], v[158:161], v[188:191], v[118:121]
	v_mfma_f32_16x16x32_bf16 v[102:105], v[150:153], v[210:213], v[102:105]
	v_mfma_f32_16x16x32_bf16 v[98:101], v[158:161], v[210:213], v[98:101]
	v_mfma_f32_16x16x32_bf16 v[86:89], v[150:153], v[218:221], v[86:89]
	v_mfma_f32_16x16x32_bf16 v[82:85], v[158:161], v[218:221], v[82:85]
	v_mfma_f32_16x16x32_bf16 v[70:73], v[150:153], v[226:229], v[70:73]
	v_mfma_f32_16x16x32_bf16 v[66:69], v[158:161], v[226:229], v[66:69]
	s_setprio 0
	s_barrier
	s_add_i32 s0, s79, 0x18000
	s_mov_b32 m0, s0
	ds_read_b128 v[184:187], v199 offset:49152
	ds_read_b128 v[188:191], v199 offset:50176
	ds_read_b128 v[206:209], v199 offset:51200
	ds_read_b128 v[210:213], v199 offset:52224
	s_add_u32 s98, s8, 0x80
	s_addc_u32 s99, s9, 0
	global_load_lds_dwordx4 v164, s[98:99]
	s_add_i32 m0, s0, 0x2000
	s_add_u32 s8, s8, 0x40080
	s_addc_u32 s9, s9, 0
	s_add_i32 s0, s79, 0x1c000
	global_load_lds_dwordx4 v168, s[98:99]
	s_mov_b32 m0, s0
	ds_read_b128 v[214:217], v199 offset:53248
	global_load_lds_dwordx4 v164, s[8:9]
	s_add_i32 m0, s0, 0x2000
	ds_read_b128 v[218:221], v199 offset:54272
	global_load_lds_dwordx4 v168, s[8:9]
	s_add_u32 s98, s10, 0xfffc0080
	s_addc_u32 s99, s11, -1
	s_mov_b32 m0, s84
	ds_read_b128 v[222:225], v199 offset:55296
	global_load_lds_dwordx4 v162, s[98:99]
	s_mov_b32 m0, s85
	ds_read_b128 v[226:229], v199 offset:56320
	global_load_lds_dwordx4 v166, s[98:99]
	s_waitcnt vmcnt(8)
	s_waitcnt lgkmcnt(0)
	s_barrier
	s_setprio 1
	v_mfma_f32_16x16x32_bf16 v[62:65], v[114:117], v[184:187], v[62:65]
	v_mfma_f32_16x16x32_bf16 v[58:61], v[138:141], v[184:187], v[58:61]
	v_mfma_f32_16x16x32_bf16 v[46:49], v[114:117], v[206:209], v[46:49]
	v_mfma_f32_16x16x32_bf16 v[42:45], v[138:141], v[206:209], v[42:45]
	v_mfma_f32_16x16x32_bf16 v[30:33], v[114:117], v[214:217], v[30:33]
	v_mfma_f32_16x16x32_bf16 v[26:29], v[138:141], v[214:217], v[26:29]
	v_mfma_f32_16x16x32_bf16 v[14:17], v[114:117], v[222:225], v[14:17]
	v_mfma_f32_16x16x32_bf16 v[10:13], v[138:141], v[222:225], v[10:13]
	v_mfma_f32_16x16x32_bf16 v[62:65], v[134:137], v[188:191], v[62:65]
	v_mfma_f32_16x16x32_bf16 v[58:61], v[142:145], v[188:191], v[58:61]
	v_mfma_f32_16x16x32_bf16 v[46:49], v[134:137], v[210:213], v[46:49]
	v_mfma_f32_16x16x32_bf16 v[42:45], v[142:145], v[210:213], v[42:45]
	v_mfma_f32_16x16x32_bf16 v[30:33], v[134:137], v[218:221], v[30:33]
	v_mfma_f32_16x16x32_bf16 v[26:29], v[142:145], v[218:221], v[26:29]
	v_mfma_f32_16x16x32_bf16 v[14:17], v[134:137], v[226:229], v[14:17]
	v_mfma_f32_16x16x32_bf16 v[10:13], v[142:145], v[226:229], v[10:13]
	v_mfma_f32_16x16x32_bf16 v[54:57], v[146:149], v[184:187], v[54:57]
	v_mfma_f32_16x16x32_bf16 v[50:53], v[154:157], v[184:187], v[50:53]
	v_mfma_f32_16x16x32_bf16 v[38:41], v[146:149], v[206:209], v[38:41]
	v_mfma_f32_16x16x32_bf16 v[34:37], v[154:157], v[206:209], v[34:37]
	v_mfma_f32_16x16x32_bf16 v[22:25], v[146:149], v[214:217], v[22:25]
	v_mfma_f32_16x16x32_bf16 v[18:21], v[154:157], v[214:217], v[18:21]
	v_mfma_f32_16x16x32_bf16 v[6:9], v[146:149], v[222:225], v[6:9]
	v_mfma_f32_16x16x32_bf16 v[2:5], v[154:157], v[222:225], v[2:5]
	v_mfma_f32_16x16x32_bf16 v[54:57], v[150:153], v[188:191], v[54:57]
	v_mfma_f32_16x16x32_bf16 v[50:53], v[158:161], v[188:191], v[50:53]
	v_mfma_f32_16x16x32_bf16 v[38:41], v[150:153], v[210:213], v[38:41]
	v_mfma_f32_16x16x32_bf16 v[34:37], v[158:161], v[210:213], v[34:37]
	v_mfma_f32_16x16x32_bf16 v[22:25], v[150:153], v[218:221], v[22:25]
	v_mfma_f32_16x16x32_bf16 v[18:21], v[158:161], v[218:221], v[18:21]
	v_mfma_f32_16x16x32_bf16 v[6:9], v[150:153], v[226:229], v[6:9]
	v_mfma_f32_16x16x32_bf16 v[2:5], v[158:161], v[226:229], v[2:5]
	s_setprio 0
	s_barrier
	s_add_i32 s26, s26, 2
	s_add_u32 s6, s6, 0x100
	s_addc_u32 s7, s7, 0
	s_add_u32 s24, s24, 0x100
	s_addc_u32 s25, s25, 0
	s_cmp_gt_u32 s26, 13
	s_cbranch_scc1 .Lpeel_x1
.LBB0_368:
	ds_read_b128 v[114:117], v197
	ds_read_b128 v[134:137], v197 offset:1024
	ds_read_b128 v[138:141], v197 offset:2048
	ds_read_b128 v[142:145], v197 offset:3072
	ds_read_b128 v[146:149], v198
	ds_read_b128 v[150:153], v198 offset:1024
	ds_read_b128 v[154:157], v198 offset:2048
	ds_read_b128 v[158:161], v198 offset:3072
	s_add_u32 s0, s6, 0xfffc0080
	s_addc_u32 s8, s7, -1
	s_cmp_eq_u32 s26, 12
	s_cselect_b32 s11, s2, s8
	s_cselect_b32 s10, s3, s0
	s_cselect_b32 s9, s12, s25
	s_cselect_b32 s8, s13, s24
	s_add_i32 m0, s31, 0xc000
	ds_read_b128 v[184:187], v199
	ds_read_b128 v[188:191], v199 offset:1024
	ds_read_b128 v[206:209], v199 offset:2048
	ds_read_b128 v[210:213], v199 offset:3072
	ds_read_b128 v[214:217], v199 offset:4096
	ds_read_b128 v[218:221], v199 offset:5120
	ds_read_b128 v[222:225], v199 offset:6144
	global_load_lds_dwordx4 v180, s[6:7]
	s_add_i32 m0, s31, 0xe000
	ds_read_b128 v[226:229], v199 offset:7168
	global_load_lds_dwordx4 v182, s[6:7]
	s_waitcnt vmcnt(8)
	s_waitcnt lgkmcnt(0)
	s_barrier
	s_setprio 1
	v_mfma_f32_16x16x32_bf16 v[130:133], v[114:117], v[184:187], v[130:133]
	v_mfma_f32_16x16x32_bf16 v[126:129], v[138:141], v[184:187], v[126:129]
	v_mfma_f32_16x16x32_bf16 v[110:113], v[114:117], v[206:209], v[110:113]
	v_mfma_f32_16x16x32_bf16 v[106:109], v[138:141], v[206:209], v[106:109]
	v_mfma_f32_16x16x32_bf16 v[94:97], v[114:117], v[214:217], v[94:97]
	v_mfma_f32_16x16x32_bf16 v[90:93], v[138:141], v[214:217], v[90:93]
	v_mfma_f32_16x16x32_bf16 v[78:81], v[114:117], v[222:225], v[78:81]
	v_mfma_f32_16x16x32_bf16 v[74:77], v[138:141], v[222:225], v[74:77]
	v_mfma_f32_16x16x32_bf16 v[130:133], v[134:137], v[188:191], v[130:133]
	v_mfma_f32_16x16x32_bf16 v[126:129], v[142:145], v[188:191], v[126:129]
	v_mfma_f32_16x16x32_bf16 v[110:113], v[134:137], v[210:213], v[110:113]
	v_mfma_f32_16x16x32_bf16 v[106:109], v[142:145], v[210:213], v[106:109]
	v_mfma_f32_16x16x32_bf16 v[94:97], v[134:137], v[218:221], v[94:97]
	v_mfma_f32_16x16x32_bf16 v[90:93], v[142:145], v[218:221], v[90:93]
	v_mfma_f32_16x16x32_bf16 v[78:81], v[134:137], v[226:229], v[78:81]
	v_mfma_f32_16x16x32_bf16 v[74:77], v[142:145], v[226:229], v[74:77]
	v_mfma_f32_16x16x32_bf16 v[122:125], v[146:149], v[184:187], v[122:125]
	v_mfma_f32_16x16x32_bf16 v[118:121], v[154:157], v[184:187], v[118:121]
	v_mfma_f32_16x16x32_bf16 v[102:105], v[146:149], v[206:209], v[102:105]
	v_mfma_f32_16x16x32_bf16 v[98:101], v[154:157], v[206:209], v[98:101]
	v_mfma_f32_16x16x32_bf16 v[86:89], v[146:149], v[214:217], v[86:89]
	v_mfma_f32_16x16x32_bf16 v[82:85], v[154:157], v[214:217], v[82:85]
	v_mfma_f32_16x16x32_bf16 v[70:73], v[146:149], v[222:225], v[70:73]
	v_mfma_f32_16x16x32_bf16 v[66:69], v[154:157], v[222:225], v[66:69]
	v_mfma_f32_16x16x32_bf16 v[122:125], v[150:153], v[188:191], v[122:125]
	v_mfma_f32_16x16x32_bf16 v[118:121], v[158:161], v[188:191], v[118:121]
	v_mfma_f32_16x16x32_bf16 v[102:105], v[150:153], v[210:213], v[102:105]
	v_mfma_f32_16x16x32_bf16 v[98:101], v[158:161], v[210:213], v[98:101]
	v_mfma_f32_16x16x32_bf16 v[86:89], v[150:153], v[218:221], v[86:89]
	v_mfma_f32_16x16x32_bf16 v[82:85], v[158:161], v[218:221], v[82:85]
	v_mfma_f32_16x16x32_bf16 v[70:73], v[150:153], v[226:229], v[70:73]
	v_mfma_f32_16x16x32_bf16 v[66:69], v[158:161], v[226:229], v[66:69]
	s_setprio 0
	s_barrier
	s_add_i32 s0, s89, s79
	s_mov_b32 m0, s0
	ds_read_b128 v[184:187], v199 offset:16384
	ds_read_b128 v[188:191], v199 offset:17408
	ds_read_b128 v[206:209], v199 offset:18432
	ds_read_b128 v[210:213], v199 offset:19456
	global_load_lds_dwordx4 v164, s[8:9]
	s_add_i32 m0, s0, 0x2000
	s_add_u32 s62, s8, 0x40000
	s_addc_u32 s63, s9, 0
	s_add_i32 s0, s90, s79
	global_load_lds_dwordx4 v168, s[8:9]
	s_mov_b32 m0, s0
	ds_read_b128 v[214:217], v199 offset:20480
	global_load_lds_dwordx4 v164, s[62:63]
	s_add_i32 m0, s0, 0x2000
	ds_read_b128 v[218:221], v199 offset:21504
	global_load_lds_dwordx4 v168, s[62:63]
	s_mov_b32 m0, s31
	ds_read_b128 v[222:225], v199 offset:22528
	global_load_lds_dwordx4 v162, s[10:11]
	s_mov_b32 m0, s80
	ds_read_b128 v[226:229], v199 offset:23552
	global_load_lds_dwordx4 v166, s[10:11]
	s_waitcnt vmcnt(8)
	s_waitcnt lgkmcnt(0)
	s_barrier
	s_setprio 1
	v_mfma_f32_16x16x32_bf16 v[62:65], v[114:117], v[184:187], v[62:65]
	v_mfma_f32_16x16x32_bf16 v[58:61], v[138:141], v[184:187], v[58:61]
	v_mfma_f32_16x16x32_bf16 v[46:49], v[114:117], v[206:209], v[46:49]
	v_mfma_f32_16x16x32_bf16 v[42:45], v[138:141], v[206:209], v[42:45]
	v_mfma_f32_16x16x32_bf16 v[30:33], v[114:117], v[214:217], v[30:33]
	v_mfma_f32_16x16x32_bf16 v[26:29], v[138:141], v[214:217], v[26:29]
	v_mfma_f32_16x16x32_bf16 v[14:17], v[114:117], v[222:225], v[14:17]
	v_mfma_f32_16x16x32_bf16 v[10:13], v[138:141], v[222:225], v[10:13]
	v_mfma_f32_16x16x32_bf16 v[62:65], v[134:137], v[188:191], v[62:65]
	v_mfma_f32_16x16x32_bf16 v[58:61], v[142:145], v[188:191], v[58:61]
	v_mfma_f32_16x16x32_bf16 v[46:49], v[134:137], v[210:213], v[46:49]
	v_mfma_f32_16x16x32_bf16 v[42:45], v[142:145], v[210:213], v[42:45]
	v_mfma_f32_16x16x32_bf16 v[30:33], v[134:137], v[218:221], v[30:33]
	v_mfma_f32_16x16x32_bf16 v[26:29], v[142:145], v[218:221], v[26:29]
	v_mfma_f32_16x16x32_bf16 v[14:17], v[134:137], v[226:229], v[14:17]
	v_mfma_f32_16x16x32_bf16 v[10:13], v[142:145], v[226:229], v[10:13]
	v_mfma_f32_16x16x32_bf16 v[54:57], v[146:149], v[184:187], v[54:57]
	v_mfma_f32_16x16x32_bf16 v[50:53], v[154:157], v[184:187], v[50:53]
	v_mfma_f32_16x16x32_bf16 v[38:41], v[146:149], v[206:209], v[38:41]
	v_mfma_f32_16x16x32_bf16 v[34:37], v[154:157], v[206:209], v[34:37]
	v_mfma_f32_16x16x32_bf16 v[22:25], v[146:149], v[214:217], v[22:25]
	v_mfma_f32_16x16x32_bf16 v[18:21], v[154:157], v[214:217], v[18:21]
	v_mfma_f32_16x16x32_bf16 v[6:9], v[146:149], v[222:225], v[6:9]
	v_mfma_f32_16x16x32_bf16 v[2:5], v[154:157], v[222:225], v[2:5]
	v_mfma_f32_16x16x32_bf16 v[54:57], v[150:153], v[188:191], v[54:57]
	v_mfma_f32_16x16x32_bf16 v[50:53], v[158:161], v[188:191], v[50:53]
	v_mfma_f32_16x16x32_bf16 v[38:41], v[150:153], v[210:213], v[38:41]
	v_mfma_f32_16x16x32_bf16 v[34:37], v[158:161], v[210:213], v[34:37]
	v_mfma_f32_16x16x32_bf16 v[22:25], v[150:153], v[218:221], v[22:25]
	v_mfma_f32_16x16x32_bf16 v[18:21], v[158:161], v[218:221], v[18:21]
	v_mfma_f32_16x16x32_bf16 v[6:9], v[150:153], v[226:229], v[6:9]
	v_mfma_f32_16x16x32_bf16 v[2:5], v[158:161], v[226:229], v[2:5]
	s_setprio 0
	s_barrier
	ds_read_b128 v[114:117], v254
	ds_read_b128 v[134:137], v254 offset:1024
	ds_read_b128 v[138:141], v254 offset:2048
	ds_read_b128 v[142:145], v254 offset:3072
	ds_read_b128 v[146:149], v255
	ds_read_b128 v[150:153], v255 offset:1024
	ds_read_b128 v[154:157], v255 offset:2048
	ds_read_b128 v[158:161], v255 offset:3072
	s_add_u32 s10, s10, 0x40000
	s_addc_u32 s11, s11, 0
	s_mov_b32 m0, s81
	ds_read_b128 v[184:187], v199 offset:32768
	ds_read_b128 v[188:191], v199 offset:33792
	ds_read_b128 v[206:209], v199 offset:34816
	ds_read_b128 v[210:213], v199 offset:35840
	ds_read_b128 v[214:217], v199 offset:36864
	ds_read_b128 v[218:221], v199 offset:37888
	ds_read_b128 v[222:225], v199 offset:38912
	global_load_lds_dwordx4 v162, s[10:11]
	s_mov_b32 m0, s82
	ds_read_b128 v[226:229], v199 offset:39936
	global_load_lds_dwordx4 v166, s[10:11]
	s_waitcnt vmcnt(8)
	s_waitcnt lgkmcnt(0)
	s_barrier
	s_setprio 1
	v_mfma_f32_16x16x32_bf16 v[130:133], v[114:117], v[184:187], v[130:133]
	v_mfma_f32_16x16x32_bf16 v[126:129], v[138:141], v[184:187], v[126:129]
	v_mfma_f32_16x16x32_bf16 v[110:113], v[114:117], v[206:209], v[110:113]
	v_mfma_f32_16x16x32_bf16 v[106:109], v[138:141], v[206:209], v[106:109]
	v_mfma_f32_16x16x32_bf16 v[94:97], v[114:117], v[214:217], v[94:97]
	v_mfma_f32_16x16x32_bf16 v[90:93], v[138:141], v[214:217], v[90:93]
	v_mfma_f32_16x16x32_bf16 v[78:81], v[114:117], v[222:225], v[78:81]
	v_mfma_f32_16x16x32_bf16 v[74:77], v[138:141], v[222:225], v[74:77]
	v_mfma_f32_16x16x32_bf16 v[130:133], v[134:137], v[188:191], v[130:133]
	v_mfma_f32_16x16x32_bf16 v[126:129], v[142:145], v[188:191], v[126:129]
	v_mfma_f32_16x16x32_bf16 v[110:113], v[134:137], v[210:213], v[110:113]
	v_mfma_f32_16x16x32_bf16 v[106:109], v[142:145], v[210:213], v[106:109]
	v_mfma_f32_16x16x32_bf16 v[94:97], v[134:137], v[218:221], v[94:97]
	v_mfma_f32_16x16x32_bf16 v[90:93], v[142:145], v[218:221], v[90:93]
	v_mfma_f32_16x16x32_bf16 v[78:81], v[134:137], v[226:229], v[78:81]
	v_mfma_f32_16x16x32_bf16 v[74:77], v[142:145], v[226:229], v[74:77]
	v_mfma_f32_16x16x32_bf16 v[122:125], v[146:149], v[184:187], v[122:125]
	v_mfma_f32_16x16x32_bf16 v[118:121], v[154:157], v[184:187], v[118:121]
	v_mfma_f32_16x16x32_bf16 v[102:105], v[146:149], v[206:209], v[102:105]
	v_mfma_f32_16x16x32_bf16 v[98:101], v[154:157], v[206:209], v[98:101]
	v_mfma_f32_16x16x32_bf16 v[86:89], v[146:149], v[214:217], v[86:89]
	v_mfma_f32_16x16x32_bf16 v[82:85], v[154:157], v[214:217], v[82:85]
	v_mfma_f32_16x16x32_bf16 v[70:73], v[146:149], v[222:225], v[70:73]
	v_mfma_f32_16x16x32_bf16 v[66:69], v[154:157], v[222:225], v[66:69]
	v_mfma_f32_16x16x32_bf16 v[122:125], v[150:153], v[188:191], v[122:125]
	v_mfma_f32_16x16x32_bf16 v[118:121], v[158:161], v[188:191], v[118:121]
	v_mfma_f32_16x16x32_bf16 v[102:105], v[150:153], v[210:213], v[102:105]
	v_mfma_f32_16x16x32_bf16 v[98:101], v[158:161], v[210:213], v[98:101]
	v_mfma_f32_16x16x32_bf16 v[86:89], v[150:153], v[218:221], v[86:89]
	v_mfma_f32_16x16x32_bf16 v[82:85], v[158:161], v[218:221], v[82:85]
	v_mfma_f32_16x16x32_bf16 v[70:73], v[150:153], v[226:229], v[70:73]
	v_mfma_f32_16x16x32_bf16 v[66:69], v[158:161], v[226:229], v[66:69]
	s_setprio 0
	s_barrier
	s_add_i32 s0, s79, 0x18000
	s_mov_b32 m0, s0
	ds_read_b128 v[184:187], v199 offset:49152
	ds_read_b128 v[188:191], v199 offset:50176
	ds_read_b128 v[206:209], v199 offset:51200
	ds_read_b128 v[210:213], v199 offset:52224
	s_add_u32 s98, s8, 0x80
	s_addc_u32 s99, s9, 0
	global_load_lds_dwordx4 v164, s[98:99]
	s_add_i32 m0, s0, 0x2000
	s_add_u32 s8, s8, 0x40080
	s_addc_u32 s9, s9, 0
	s_add_i32 s0, s79, 0x1c000
	global_load_lds_dwordx4 v168, s[98:99]
	s_mov_b32 m0, s0
	ds_read_b128 v[214:217], v199 offset:53248
	global_load_lds_dwordx4 v164, s[8:9]
	s_add_i32 m0, s0, 0x2000
	ds_read_b128 v[218:221], v199 offset:54272
	global_load_lds_dwordx4 v168, s[8:9]
	s_add_u32 s98, s10, 0xfffc0080
	s_addc_u32 s99, s11, -1
	s_mov_b32 m0, s84
	ds_read_b128 v[222:225], v199 offset:55296
	global_load_lds_dwordx4 v162, s[98:99]
	s_mov_b32 m0, s85
	ds_read_b128 v[226:229], v199 offset:56320
	global_load_lds_dwordx4 v166, s[98:99]
	s_waitcnt vmcnt(8)
	s_waitcnt lgkmcnt(0)
	s_barrier
	s_setprio 1
	v_mfma_f32_16x16x32_bf16 v[62:65], v[114:117], v[184:187], v[62:65]
	v_mfma_f32_16x16x32_bf16 v[58:61], v[138:141], v[184:187], v[58:61]
	v_mfma_f32_16x16x32_bf16 v[46:49], v[114:117], v[206:209], v[46:49]
	v_mfma_f32_16x16x32_bf16 v[42:45], v[138:141], v[206:209], v[42:45]
	v_mfma_f32_16x16x32_bf16 v[30:33], v[114:117], v[214:217], v[30:33]
	v_mfma_f32_16x16x32_bf16 v[26:29], v[138:141], v[214:217], v[26:29]
	v_mfma_f32_16x16x32_bf16 v[14:17], v[114:117], v[222:225], v[14:17]
	v_mfma_f32_16x16x32_bf16 v[10:13], v[138:141], v[222:225], v[10:13]
	v_mfma_f32_16x16x32_bf16 v[62:65], v[134:137], v[188:191], v[62:65]
	v_mfma_f32_16x16x32_bf16 v[58:61], v[142:145], v[188:191], v[58:61]
	v_mfma_f32_16x16x32_bf16 v[46:49], v[134:137], v[210:213], v[46:49]
	v_mfma_f32_16x16x32_bf16 v[42:45], v[142:145], v[210:213], v[42:45]
	v_mfma_f32_16x16x32_bf16 v[30:33], v[134:137], v[218:221], v[30:33]
	v_mfma_f32_16x16x32_bf16 v[26:29], v[142:145], v[218:221], v[26:29]
	v_mfma_f32_16x16x32_bf16 v[14:17], v[134:137], v[226:229], v[14:17]
	v_mfma_f32_16x16x32_bf16 v[10:13], v[142:145], v[226:229], v[10:13]
	v_mfma_f32_16x16x32_bf16 v[54:57], v[146:149], v[184:187], v[54:57]
	v_mfma_f32_16x16x32_bf16 v[50:53], v[154:157], v[184:187], v[50:53]
	v_mfma_f32_16x16x32_bf16 v[38:41], v[146:149], v[206:209], v[38:41]
	v_mfma_f32_16x16x32_bf16 v[34:37], v[154:157], v[206:209], v[34:37]
	v_mfma_f32_16x16x32_bf16 v[22:25], v[146:149], v[214:217], v[22:25]
	v_mfma_f32_16x16x32_bf16 v[18:21], v[154:157], v[214:217], v[18:21]
	v_mfma_f32_16x16x32_bf16 v[6:9], v[146:149], v[222:225], v[6:9]
	v_mfma_f32_16x16x32_bf16 v[2:5], v[154:157], v[222:225], v[2:5]
	v_mfma_f32_16x16x32_bf16 v[54:57], v[150:153], v[188:191], v[54:57]
	v_mfma_f32_16x16x32_bf16 v[50:53], v[158:161], v[188:191], v[50:53]
	v_mfma_f32_16x16x32_bf16 v[38:41], v[150:153], v[210:213], v[38:41]
	v_mfma_f32_16x16x32_bf16 v[34:37], v[158:161], v[210:213], v[34:37]
	v_mfma_f32_16x16x32_bf16 v[22:25], v[150:153], v[218:221], v[22:25]
	v_mfma_f32_16x16x32_bf16 v[18:21], v[158:161], v[218:221], v[18:21]
	v_mfma_f32_16x16x32_bf16 v[6:9], v[150:153], v[226:229], v[6:9]
	v_mfma_f32_16x16x32_bf16 v[2:5], v[158:161], v[226:229], v[2:5]
	s_setprio 0
	s_barrier
	s_add_i32 s26, s26, 2
	s_add_u32 s6, s6, 0x100
	s_addc_u32 s7, s7, 0
	s_add_u32 s24, s24, 0x100
	s_addc_u32 s25, s25, 0
	s_cmp_gt_u32 s26, 13
	s_cbranch_scc0 .LBB0_368

.LBB0_990:
	s_ashr_i32 s37, s36, 31
	s_lshl_b64 s[2:3], s[36:37], 19
	s_add_u32 s40, s48, s2
	s_addc_u32 s41, s49, s3
	s_and_b64 s[2:3], s[44:45], exec
	s_cselect_b32 s1, s41, s9
	s_cselect_b32 s2, s40, s8
	s_ashr_i32 s39, s38, 31
	s_lshl_b64 s[4:5], s[38:39], 19
	s_add_u32 s42, s50, s4
	s_addc_u32 s43, s51, s5
	s_and_b64 s[4:5], s[44:45], exec
	s_cselect_b32 s3, s43, s11
	s_cselect_b32 s4, s42, s10
	s_add_u32 s8, s8, 0x40080
	s_addc_u32 s9, s9, 0
	s_add_u32 s5, s10, 0x100
	s_addc_u32 s7, s11, 0
	s_mov_b32 s22, -2
	v_add_u32_e32 v254, 0x18000, v213
	v_add_u32_e32 v255, 0x1c000, v213
	ds_read_b128 v[66:69], v219
	ds_read_b128 v[70:73], v219 offset:1024
	ds_read_b128 v[86:89], v219 offset:2048
	ds_read_b128 v[106:109], v219 offset:3072
	ds_read_b128 v[146:149], v220
	ds_read_b128 v[150:153], v220 offset:1024
	ds_read_b128 v[154:157], v220 offset:2048
	ds_read_b128 v[158:161], v220 offset:3072
	s_add_u32 s10, s8, 0xfffc0080
	s_addc_u32 s11, s9, -1
	s_cmp_eq_u32 s22, 12
	s_cselect_b32 s45, s1, s11
	s_cselect_b32 s44, s2, s10
	s_cselect_b32 s11, s3, s7
	s_cselect_b32 s10, s4, s5
	s_add_i32 m0, s54, 0xc000
	ds_read_b128 v[162:165], v221
	ds_read_b128 v[166:169], v221 offset:1024
	ds_read_b128 v[170:173], v221 offset:2048
	ds_read_b128 v[174:177], v221 offset:3072
	ds_read_b128 v[196:199], v221 offset:4096
	ds_read_b128 v[200:203], v221 offset:5120
	ds_read_b128 v[204:207], v221 offset:6144
	global_load_lds_dwordx4 v192, s[8:9]
	s_add_i32 m0, s54, 0xe000
	ds_read_b128 v[208:211], v221 offset:7168
	global_load_lds_dwordx4 v194, s[8:9]
	s_waitcnt vmcnt(8)
	s_waitcnt lgkmcnt(0)
	s_barrier
	s_setprio 1
	v_mfma_f32_16x16x32_bf16 v[142:145], v[66:69], v[162:165], 0
	v_mfma_f32_16x16x32_bf16 v[134:137], v[86:89], v[162:165], 0
	v_mfma_f32_16x16x32_bf16 v[126:129], v[66:69], v[170:173], 0
	v_mfma_f32_16x16x32_bf16 v[122:125], v[86:89], v[170:173], 0
	v_mfma_f32_16x16x32_bf16 v[110:113], v[66:69], v[196:199], 0
	v_mfma_f32_16x16x32_bf16 v[102:105], v[86:89], v[196:199], 0
	v_mfma_f32_16x16x32_bf16 v[90:93], v[66:69], v[204:207], 0
	v_mfma_f32_16x16x32_bf16 v[82:85], v[86:89], v[204:207], 0
	v_mfma_f32_16x16x32_bf16 v[142:145], v[70:73], v[166:169], v[142:145]
	v_mfma_f32_16x16x32_bf16 v[134:137], v[106:109], v[166:169], v[134:137]
	v_mfma_f32_16x16x32_bf16 v[126:129], v[70:73], v[174:177], v[126:129]
	v_mfma_f32_16x16x32_bf16 v[122:125], v[106:109], v[174:177], v[122:125]
	v_mfma_f32_16x16x32_bf16 v[110:113], v[70:73], v[200:203], v[110:113]
	v_mfma_f32_16x16x32_bf16 v[102:105], v[106:109], v[200:203], v[102:105]
	v_mfma_f32_16x16x32_bf16 v[90:93], v[70:73], v[208:211], v[90:93]
	v_mfma_f32_16x16x32_bf16 v[82:85], v[106:109], v[208:211], v[82:85]
	v_mfma_f32_16x16x32_bf16 v[138:141], v[146:149], v[162:165], 0
	v_mfma_f32_16x16x32_bf16 v[130:133], v[154:157], v[162:165], 0
	v_mfma_f32_16x16x32_bf16 v[118:121], v[146:149], v[170:173], 0
	v_mfma_f32_16x16x32_bf16 v[114:117], v[154:157], v[170:173], 0
	v_mfma_f32_16x16x32_bf16 v[98:101], v[146:149], v[196:199], 0
	v_mfma_f32_16x16x32_bf16 v[94:97], v[154:157], v[196:199], 0
	v_mfma_f32_16x16x32_bf16 v[78:81], v[146:149], v[204:207], 0
	v_mfma_f32_16x16x32_bf16 v[74:77], v[154:157], v[204:207], 0
	v_mfma_f32_16x16x32_bf16 v[138:141], v[150:153], v[166:169], v[138:141]
	v_mfma_f32_16x16x32_bf16 v[130:133], v[158:161], v[166:169], v[130:133]
	v_mfma_f32_16x16x32_bf16 v[118:121], v[150:153], v[174:177], v[118:121]
	v_mfma_f32_16x16x32_bf16 v[114:117], v[158:161], v[174:177], v[114:117]
	v_mfma_f32_16x16x32_bf16 v[98:101], v[150:153], v[200:203], v[98:101]
	v_mfma_f32_16x16x32_bf16 v[94:97], v[158:161], v[200:203], v[94:97]
	v_mfma_f32_16x16x32_bf16 v[78:81], v[150:153], v[208:211], v[78:81]
	v_mfma_f32_16x16x32_bf16 v[74:77], v[158:161], v[208:211], v[74:77]
	s_setprio 0
	s_barrier
	s_add_i32 s37, s62, s53
	s_mov_b32 m0, s37
	ds_read_b128 v[162:165], v221 offset:16384
	ds_read_b128 v[166:169], v221 offset:17408
	ds_read_b128 v[170:173], v221 offset:18432
	ds_read_b128 v[174:177], v221 offset:19456
	global_load_lds_dwordx4 v184, s[10:11]
	s_add_i32 m0, s37, 0x2000
	s_add_u32 s46, s10, 0x40000
	s_addc_u32 s47, s11, 0
	s_add_i32 s37, s63, s53
	global_load_lds_dwordx4 v188, s[10:11]
	s_mov_b32 m0, s37
	ds_read_b128 v[196:199], v221 offset:20480
	global_load_lds_dwordx4 v184, s[46:47]
	s_add_i32 m0, s37, 0x2000
	ds_read_b128 v[200:203], v221 offset:21504
	global_load_lds_dwordx4 v188, s[46:47]
	s_mov_b32 m0, s54
	ds_read_b128 v[204:207], v221 offset:22528
	global_load_lds_dwordx4 v182, s[44:45]
	s_mov_b32 m0, s55
	ds_read_b128 v[208:211], v221 offset:23552
	global_load_lds_dwordx4 v186, s[44:45]
	s_waitcnt vmcnt(8)
	s_waitcnt lgkmcnt(0)
	s_barrier
	s_setprio 1
	v_mfma_f32_16x16x32_bf16 v[62:65], v[66:69], v[162:165], 0
	v_mfma_f32_16x16x32_bf16 v[54:57], v[86:89], v[162:165], 0
	v_mfma_f32_16x16x32_bf16 v[46:49], v[66:69], v[170:173], 0
	v_mfma_f32_16x16x32_bf16 v[42:45], v[86:89], v[170:173], 0
	v_mfma_f32_16x16x32_bf16 v[30:33], v[66:69], v[196:199], 0
	v_mfma_f32_16x16x32_bf16 v[26:29], v[86:89], v[196:199], 0
	v_mfma_f32_16x16x32_bf16 v[14:17], v[66:69], v[204:207], 0
	v_mfma_f32_16x16x32_bf16 v[10:13], v[86:89], v[204:207], 0
	v_mfma_f32_16x16x32_bf16 v[62:65], v[70:73], v[166:169], v[62:65]
	v_mfma_f32_16x16x32_bf16 v[54:57], v[106:109], v[166:169], v[54:57]
	v_mfma_f32_16x16x32_bf16 v[46:49], v[70:73], v[174:177], v[46:49]
	v_mfma_f32_16x16x32_bf16 v[42:45], v[106:109], v[174:177], v[42:45]
	v_mfma_f32_16x16x32_bf16 v[30:33], v[70:73], v[200:203], v[30:33]
	v_mfma_f32_16x16x32_bf16 v[26:29], v[106:109], v[200:203], v[26:29]
	v_mfma_f32_16x16x32_bf16 v[14:17], v[70:73], v[208:211], v[14:17]
	v_mfma_f32_16x16x32_bf16 v[10:13], v[106:109], v[208:211], v[10:13]
	v_mfma_f32_16x16x32_bf16 v[58:61], v[146:149], v[162:165], 0
	v_mfma_f32_16x16x32_bf16 v[50:53], v[154:157], v[162:165], 0
	v_mfma_f32_16x16x32_bf16 v[38:41], v[146:149], v[170:173], 0
	v_mfma_f32_16x16x32_bf16 v[34:37], v[154:157], v[170:173], 0
	v_mfma_f32_16x16x32_bf16 v[22:25], v[146:149], v[196:199], 0
	v_mfma_f32_16x16x32_bf16 v[18:21], v[154:157], v[196:199], 0
	v_mfma_f32_16x16x32_bf16 v[6:9], v[146:149], v[204:207], 0
	v_mfma_f32_16x16x32_bf16 v[2:5], v[154:157], v[204:207], 0
	v_mfma_f32_16x16x32_bf16 v[58:61], v[150:153], v[166:169], v[58:61]
	v_mfma_f32_16x16x32_bf16 v[50:53], v[158:161], v[166:169], v[50:53]
	v_mfma_f32_16x16x32_bf16 v[38:41], v[150:153], v[174:177], v[38:41]
	v_mfma_f32_16x16x32_bf16 v[34:37], v[158:161], v[174:177], v[34:37]
	v_mfma_f32_16x16x32_bf16 v[22:25], v[150:153], v[200:203], v[22:25]
	v_mfma_f32_16x16x32_bf16 v[18:21], v[158:161], v[200:203], v[18:21]
	v_mfma_f32_16x16x32_bf16 v[6:9], v[150:153], v[208:211], v[6:9]
	v_mfma_f32_16x16x32_bf16 v[2:5], v[158:161], v[208:211], v[2:5]
	s_setprio 0
	s_barrier
	ds_read_b128 v[66:69], v254
	ds_read_b128 v[70:73], v254 offset:1024
	ds_read_b128 v[86:89], v254 offset:2048
	ds_read_b128 v[106:109], v254 offset:3072
	ds_read_b128 v[146:149], v255
	ds_read_b128 v[150:153], v255 offset:1024
	ds_read_b128 v[154:157], v255 offset:2048
	ds_read_b128 v[158:161], v255 offset:3072
	s_add_u32 s44, s44, 0x40000
	s_addc_u32 s45, s45, 0
	s_mov_b32 m0, s56
	ds_read_b128 v[162:165], v221 offset:32768
	ds_read_b128 v[166:169], v221 offset:33792
	ds_read_b128 v[170:173], v221 offset:34816
	ds_read_b128 v[174:177], v221 offset:35840
	ds_read_b128 v[196:199], v221 offset:36864
	ds_read_b128 v[200:203], v221 offset:37888
	ds_read_b128 v[204:207], v221 offset:38912
	global_load_lds_dwordx4 v182, s[44:45]
	s_mov_b32 m0, s57
	ds_read_b128 v[208:211], v221 offset:39936
	global_load_lds_dwordx4 v186, s[44:45]
	s_waitcnt vmcnt(8)
	s_waitcnt lgkmcnt(0)
	s_barrier
	s_setprio 1
	v_mfma_f32_16x16x32_bf16 v[142:145], v[66:69], v[162:165], v[142:145]
	v_mfma_f32_16x16x32_bf16 v[134:137], v[86:89], v[162:165], v[134:137]
	v_mfma_f32_16x16x32_bf16 v[126:129], v[66:69], v[170:173], v[126:129]
	v_mfma_f32_16x16x32_bf16 v[122:125], v[86:89], v[170:173], v[122:125]
	v_mfma_f32_16x16x32_bf16 v[110:113], v[66:69], v[196:199], v[110:113]
	v_mfma_f32_16x16x32_bf16 v[102:105], v[86:89], v[196:199], v[102:105]
	v_mfma_f32_16x16x32_bf16 v[90:93], v[66:69], v[204:207], v[90:93]
	v_mfma_f32_16x16x32_bf16 v[82:85], v[86:89], v[204:207], v[82:85]
	v_mfma_f32_16x16x32_bf16 v[142:145], v[70:73], v[166:169], v[142:145]
	v_mfma_f32_16x16x32_bf16 v[134:137], v[106:109], v[166:169], v[134:137]
	v_mfma_f32_16x16x32_bf16 v[126:129], v[70:73], v[174:177], v[126:129]
	v_mfma_f32_16x16x32_bf16 v[122:125], v[106:109], v[174:177], v[122:125]
	v_mfma_f32_16x16x32_bf16 v[110:113], v[70:73], v[200:203], v[110:113]
	v_mfma_f32_16x16x32_bf16 v[102:105], v[106:109], v[200:203], v[102:105]
	v_mfma_f32_16x16x32_bf16 v[90:93], v[70:73], v[208:211], v[90:93]
	v_mfma_f32_16x16x32_bf16 v[82:85], v[106:109], v[208:211], v[82:85]
	v_mfma_f32_16x16x32_bf16 v[138:141], v[146:149], v[162:165], v[138:141]
	v_mfma_f32_16x16x32_bf16 v[130:133], v[154:157], v[162:165], v[130:133]
	v_mfma_f32_16x16x32_bf16 v[118:121], v[146:149], v[170:173], v[118:121]
	v_mfma_f32_16x16x32_bf16 v[114:117], v[154:157], v[170:173], v[114:117]
	v_mfma_f32_16x16x32_bf16 v[98:101], v[146:149], v[196:199], v[98:101]
	v_mfma_f32_16x16x32_bf16 v[94:97], v[154:157], v[196:199], v[94:97]
	v_mfma_f32_16x16x32_bf16 v[78:81], v[146:149], v[204:207], v[78:81]
	v_mfma_f32_16x16x32_bf16 v[74:77], v[154:157], v[204:207], v[74:77]
	v_mfma_f32_16x16x32_bf16 v[138:141], v[150:153], v[166:169], v[138:141]
	v_mfma_f32_16x16x32_bf16 v[130:133], v[158:161], v[166:169], v[130:133]
	v_mfma_f32_16x16x32_bf16 v[118:121], v[150:153], v[174:177], v[118:121]
	v_mfma_f32_16x16x32_bf16 v[114:117], v[158:161], v[174:177], v[114:117]
	v_mfma_f32_16x16x32_bf16 v[98:101], v[150:153], v[200:203], v[98:101]
	v_mfma_f32_16x16x32_bf16 v[94:97], v[158:161], v[200:203], v[94:97]
	v_mfma_f32_16x16x32_bf16 v[78:81], v[150:153], v[208:211], v[78:81]
	v_mfma_f32_16x16x32_bf16 v[74:77], v[158:161], v[208:211], v[74:77]
	s_setprio 0
	s_barrier
	s_add_i32 s37, s53, 0x18000
	s_mov_b32 m0, s37
	ds_read_b128 v[162:165], v221 offset:49152
	ds_read_b128 v[166:169], v221 offset:50176
	ds_read_b128 v[170:173], v221 offset:51200
	ds_read_b128 v[174:177], v221 offset:52224
	s_add_u32 s98, s10, 0x80
	s_addc_u32 s99, s11, 0
	global_load_lds_dwordx4 v184, s[98:99]
	s_add_i32 m0, s37, 0x2000
	s_add_u32 s10, s10, 0x40080
	s_addc_u32 s11, s11, 0
	s_add_i32 s37, s53, 0x1c000
	global_load_lds_dwordx4 v188, s[98:99]
	s_mov_b32 m0, s37
	ds_read_b128 v[196:199], v221 offset:53248
	global_load_lds_dwordx4 v184, s[10:11]
	s_add_i32 m0, s37, 0x2000
	ds_read_b128 v[200:203], v221 offset:54272
	global_load_lds_dwordx4 v188, s[10:11]
	s_add_u32 s98, s44, 0xfffc0080
	s_addc_u32 s99, s45, -1
	s_mov_b32 m0, s60
	ds_read_b128 v[204:207], v221 offset:55296
	global_load_lds_dwordx4 v182, s[98:99]
	s_mov_b32 m0, s61
	ds_read_b128 v[208:211], v221 offset:56320
	global_load_lds_dwordx4 v186, s[98:99]
	s_waitcnt vmcnt(8)
	s_waitcnt lgkmcnt(0)
	s_barrier
	s_setprio 1
	v_mfma_f32_16x16x32_bf16 v[62:65], v[66:69], v[162:165], v[62:65]
	v_mfma_f32_16x16x32_bf16 v[54:57], v[86:89], v[162:165], v[54:57]
	v_mfma_f32_16x16x32_bf16 v[46:49], v[66:69], v[170:173], v[46:49]
	v_mfma_f32_16x16x32_bf16 v[42:45], v[86:89], v[170:173], v[42:45]
	v_mfma_f32_16x16x32_bf16 v[30:33], v[66:69], v[196:199], v[30:33]
	v_mfma_f32_16x16x32_bf16 v[26:29], v[86:89], v[196:199], v[26:29]
	v_mfma_f32_16x16x32_bf16 v[14:17], v[66:69], v[204:207], v[14:17]
	v_mfma_f32_16x16x32_bf16 v[10:13], v[86:89], v[204:207], v[10:13]
	v_mfma_f32_16x16x32_bf16 v[62:65], v[70:73], v[166:169], v[62:65]
	v_mfma_f32_16x16x32_bf16 v[54:57], v[106:109], v[166:169], v[54:57]
	v_mfma_f32_16x16x32_bf16 v[46:49], v[70:73], v[174:177], v[46:49]
	v_mfma_f32_16x16x32_bf16 v[42:45], v[106:109], v[174:177], v[42:45]
	v_mfma_f32_16x16x32_bf16 v[30:33], v[70:73], v[200:203], v[30:33]
	v_mfma_f32_16x16x32_bf16 v[26:29], v[106:109], v[200:203], v[26:29]
	v_mfma_f32_16x16x32_bf16 v[14:17], v[70:73], v[208:211], v[14:17]
	v_mfma_f32_16x16x32_bf16 v[10:13], v[106:109], v[208:211], v[10:13]
	v_mfma_f32_16x16x32_bf16 v[58:61], v[146:149], v[162:165], v[58:61]
	v_mfma_f32_16x16x32_bf16 v[50:53], v[154:157], v[162:165], v[50:53]
	v_mfma_f32_16x16x32_bf16 v[38:41], v[146:149], v[170:173], v[38:41]
	v_mfma_f32_16x16x32_bf16 v[34:37], v[154:157], v[170:173], v[34:37]
	v_mfma_f32_16x16x32_bf16 v[22:25], v[146:149], v[196:199], v[22:25]
	v_mfma_f32_16x16x32_bf16 v[18:21], v[154:157], v[196:199], v[18:21]
	v_mfma_f32_16x16x32_bf16 v[6:9], v[146:149], v[204:207], v[6:9]
	v_mfma_f32_16x16x32_bf16 v[2:5], v[154:157], v[204:207], v[2:5]
	v_mfma_f32_16x16x32_bf16 v[58:61], v[150:153], v[166:169], v[58:61]
	v_mfma_f32_16x16x32_bf16 v[50:53], v[158:161], v[166:169], v[50:53]
	v_mfma_f32_16x16x32_bf16 v[38:41], v[150:153], v[174:177], v[38:41]
	v_mfma_f32_16x16x32_bf16 v[34:37], v[158:161], v[174:177], v[34:37]
	v_mfma_f32_16x16x32_bf16 v[22:25], v[150:153], v[200:203], v[22:25]
	v_mfma_f32_16x16x32_bf16 v[18:21], v[158:161], v[200:203], v[18:21]
	v_mfma_f32_16x16x32_bf16 v[6:9], v[150:153], v[208:211], v[6:9]
	v_mfma_f32_16x16x32_bf16 v[2:5], v[158:161], v[208:211], v[2:5]
	s_setprio 0
	s_barrier
	s_add_i32 s22, s22, 2
	s_add_u32 s8, s8, 0x100
	s_addc_u32 s9, s9, 0
	s_add_u32 s5, s5, 0x100
	s_addc_u32 s7, s7, 0
	s_cmp_gt_u32 s22, 13
	s_cbranch_scc1 .Lpeel_x4
.LBB0_991:
	ds_read_b128 v[66:69], v219
	ds_read_b128 v[70:73], v219 offset:1024
	ds_read_b128 v[86:89], v219 offset:2048
	ds_read_b128 v[106:109], v219 offset:3072
	ds_read_b128 v[146:149], v220
	ds_read_b128 v[150:153], v220 offset:1024
	ds_read_b128 v[154:157], v220 offset:2048
	ds_read_b128 v[158:161], v220 offset:3072
	s_add_u32 s10, s8, 0xfffc0080
	s_addc_u32 s11, s9, -1
	s_cmp_eq_u32 s22, 12
	s_cselect_b32 s45, s1, s11
	s_cselect_b32 s44, s2, s10
	s_cselect_b32 s11, s3, s7
	s_cselect_b32 s10, s4, s5
	s_add_i32 m0, s54, 0xc000
	ds_read_b128 v[162:165], v221
	ds_read_b128 v[166:169], v221 offset:1024
	ds_read_b128 v[170:173], v221 offset:2048
	ds_read_b128 v[174:177], v221 offset:3072
	ds_read_b128 v[196:199], v221 offset:4096
	ds_read_b128 v[200:203], v221 offset:5120
	ds_read_b128 v[204:207], v221 offset:6144
	global_load_lds_dwordx4 v192, s[8:9]
	s_add_i32 m0, s54, 0xe000
	ds_read_b128 v[208:211], v221 offset:7168
	global_load_lds_dwordx4 v194, s[8:9]
	s_waitcnt vmcnt(8)
	s_waitcnt lgkmcnt(0)
	s_barrier
	s_setprio 1
	v_mfma_f32_16x16x32_bf16 v[142:145], v[66:69], v[162:165], v[142:145]
	v_mfma_f32_16x16x32_bf16 v[134:137], v[86:89], v[162:165], v[134:137]
	v_mfma_f32_16x16x32_bf16 v[126:129], v[66:69], v[170:173], v[126:129]
	v_mfma_f32_16x16x32_bf16 v[122:125], v[86:89], v[170:173], v[122:125]
	v_mfma_f32_16x16x32_bf16 v[110:113], v[66:69], v[196:199], v[110:113]
	v_mfma_f32_16x16x32_bf16 v[102:105], v[86:89], v[196:199], v[102:105]
	v_mfma_f32_16x16x32_bf16 v[90:93], v[66:69], v[204:207], v[90:93]
	v_mfma_f32_16x16x32_bf16 v[82:85], v[86:89], v[204:207], v[82:85]
	v_mfma_f32_16x16x32_bf16 v[142:145], v[70:73], v[166:169], v[142:145]
	v_mfma_f32_16x16x32_bf16 v[134:137], v[106:109], v[166:169], v[134:137]
	v_mfma_f32_16x16x32_bf16 v[126:129], v[70:73], v[174:177], v[126:129]
	v_mfma_f32_16x16x32_bf16 v[122:125], v[106:109], v[174:177], v[122:125]
	v_mfma_f32_16x16x32_bf16 v[110:113], v[70:73], v[200:203], v[110:113]
	v_mfma_f32_16x16x32_bf16 v[102:105], v[106:109], v[200:203], v[102:105]
	v_mfma_f32_16x16x32_bf16 v[90:93], v[70:73], v[208:211], v[90:93]
	v_mfma_f32_16x16x32_bf16 v[82:85], v[106:109], v[208:211], v[82:85]
	v_mfma_f32_16x16x32_bf16 v[138:141], v[146:149], v[162:165], v[138:141]
	v_mfma_f32_16x16x32_bf16 v[130:133], v[154:157], v[162:165], v[130:133]
	v_mfma_f32_16x16x32_bf16 v[118:121], v[146:149], v[170:173], v[118:121]
	v_mfma_f32_16x16x32_bf16 v[114:117], v[154:157], v[170:173], v[114:117]
	v_mfma_f32_16x16x32_bf16 v[98:101], v[146:149], v[196:199], v[98:101]
	v_mfma_f32_16x16x32_bf16 v[94:97], v[154:157], v[196:199], v[94:97]
	v_mfma_f32_16x16x32_bf16 v[78:81], v[146:149], v[204:207], v[78:81]
	v_mfma_f32_16x16x32_bf16 v[74:77], v[154:157], v[204:207], v[74:77]
	v_mfma_f32_16x16x32_bf16 v[138:141], v[150:153], v[166:169], v[138:141]
	v_mfma_f32_16x16x32_bf16 v[130:133], v[158:161], v[166:169], v[130:133]
	v_mfma_f32_16x16x32_bf16 v[118:121], v[150:153], v[174:177], v[118:121]
	v_mfma_f32_16x16x32_bf16 v[114:117], v[158:161], v[174:177], v[114:117]
	v_mfma_f32_16x16x32_bf16 v[98:101], v[150:153], v[200:203], v[98:101]
	v_mfma_f32_16x16x32_bf16 v[94:97], v[158:161], v[200:203], v[94:97]
	v_mfma_f32_16x16x32_bf16 v[78:81], v[150:153], v[208:211], v[78:81]
	v_mfma_f32_16x16x32_bf16 v[74:77], v[158:161], v[208:211], v[74:77]
	s_setprio 0
	s_barrier
	s_add_i32 s37, s62, s53
	s_mov_b32 m0, s37
	ds_read_b128 v[162:165], v221 offset:16384
	ds_read_b128 v[166:169], v221 offset:17408
	ds_read_b128 v[170:173], v221 offset:18432
	ds_read_b128 v[174:177], v221 offset:19456
	global_load_lds_dwordx4 v184, s[10:11]
	s_add_i32 m0, s37, 0x2000
	s_add_u32 s46, s10, 0x40000
	s_addc_u32 s47, s11, 0
	s_add_i32 s37, s63, s53
	global_load_lds_dwordx4 v188, s[10:11]
	s_mov_b32 m0, s37
	ds_read_b128 v[196:199], v221 offset:20480
	global_load_lds_dwordx4 v184, s[46:47]
	s_add_i32 m0, s37, 0x2000
	ds_read_b128 v[200:203], v221 offset:21504
	global_load_lds_dwordx4 v188, s[46:47]
	s_mov_b32 m0, s54
	ds_read_b128 v[204:207], v221 offset:22528
	global_load_lds_dwordx4 v182, s[44:45]
	s_mov_b32 m0, s55
	ds_read_b128 v[208:211], v221 offset:23552
	global_load_lds_dwordx4 v186, s[44:45]
	s_waitcnt vmcnt(8)
	s_waitcnt lgkmcnt(0)
	s_barrier
	s_setprio 1
	v_mfma_f32_16x16x32_bf16 v[62:65], v[66:69], v[162:165], v[62:65]
	v_mfma_f32_16x16x32_bf16 v[54:57], v[86:89], v[162:165], v[54:57]
	v_mfma_f32_16x16x32_bf16 v[46:49], v[66:69], v[170:173], v[46:49]
	v_mfma_f32_16x16x32_bf16 v[42:45], v[86:89], v[170:173], v[42:45]
	v_mfma_f32_16x16x32_bf16 v[30:33], v[66:69], v[196:199], v[30:33]
	v_mfma_f32_16x16x32_bf16 v[26:29], v[86:89], v[196:199], v[26:29]
	v_mfma_f32_16x16x32_bf16 v[14:17], v[66:69], v[204:207], v[14:17]
	v_mfma_f32_16x16x32_bf16 v[10:13], v[86:89], v[204:207], v[10:13]
	v_mfma_f32_16x16x32_bf16 v[62:65], v[70:73], v[166:169], v[62:65]
	v_mfma_f32_16x16x32_bf16 v[54:57], v[106:109], v[166:169], v[54:57]
	v_mfma_f32_16x16x32_bf16 v[46:49], v[70:73], v[174:177], v[46:49]
	v_mfma_f32_16x16x32_bf16 v[42:45], v[106:109], v[174:177], v[42:45]
	v_mfma_f32_16x16x32_bf16 v[30:33], v[70:73], v[200:203], v[30:33]
	v_mfma_f32_16x16x32_bf16 v[26:29], v[106:109], v[200:203], v[26:29]
	v_mfma_f32_16x16x32_bf16 v[14:17], v[70:73], v[208:211], v[14:17]
	v_mfma_f32_16x16x32_bf16 v[10:13], v[106:109], v[208:211], v[10:13]
	v_mfma_f32_16x16x32_bf16 v[58:61], v[146:149], v[162:165], v[58:61]
	v_mfma_f32_16x16x32_bf16 v[50:53], v[154:157], v[162:165], v[50:53]
	v_mfma_f32_16x16x32_bf16 v[38:41], v[146:149], v[170:173], v[38:41]
	v_mfma_f32_16x16x32_bf16 v[34:37], v[154:157], v[170:173], v[34:37]
	v_mfma_f32_16x16x32_bf16 v[22:25], v[146:149], v[196:199], v[22:25]
	v_mfma_f32_16x16x32_bf16 v[18:21], v[154:157], v[196:199], v[18:21]
	v_mfma_f32_16x16x32_bf16 v[6:9], v[146:149], v[204:207], v[6:9]
	v_mfma_f32_16x16x32_bf16 v[2:5], v[154:157], v[204:207], v[2:5]
	v_mfma_f32_16x16x32_bf16 v[58:61], v[150:153], v[166:169], v[58:61]
	v_mfma_f32_16x16x32_bf16 v[50:53], v[158:161], v[166:169], v[50:53]
	v_mfma_f32_16x16x32_bf16 v[38:41], v[150:153], v[174:177], v[38:41]
	v_mfma_f32_16x16x32_bf16 v[34:37], v[158:161], v[174:177], v[34:37]
	v_mfma_f32_16x16x32_bf16 v[22:25], v[150:153], v[200:203], v[22:25]
	v_mfma_f32_16x16x32_bf16 v[18:21], v[158:161], v[200:203], v[18:21]
	v_mfma_f32_16x16x32_bf16 v[6:9], v[150:153], v[208:211], v[6:9]
	v_mfma_f32_16x16x32_bf16 v[2:5], v[158:161], v[208:211], v[2:5]
	s_setprio 0
	s_barrier
	ds_read_b128 v[66:69], v254
	ds_read_b128 v[70:73], v254 offset:1024
	ds_read_b128 v[86:89], v254 offset:2048
	ds_read_b128 v[106:109], v254 offset:3072
	ds_read_b128 v[146:149], v255
	ds_read_b128 v[150:153], v255 offset:1024
	ds_read_b128 v[154:157], v255 offset:2048
	ds_read_b128 v[158:161], v255 offset:3072
	s_add_u32 s44, s44, 0x40000
	s_addc_u32 s45, s45, 0
	s_mov_b32 m0, s56
	ds_read_b128 v[162:165], v221 offset:32768
	ds_read_b128 v[166:169], v221 offset:33792
	ds_read_b128 v[170:173], v221 offset:34816
	ds_read_b128 v[174:177], v221 offset:35840
	ds_read_b128 v[196:199], v221 offset:36864
	ds_read_b128 v[200:203], v221 offset:37888
	ds_read_b128 v[204:207], v221 offset:38912
	global_load_lds_dwordx4 v182, s[44:45]
	s_mov_b32 m0, s57
	ds_read_b128 v[208:211], v221 offset:39936
	global_load_lds_dwordx4 v186, s[44:45]
	s_waitcnt vmcnt(8)
	s_waitcnt lgkmcnt(0)
	s_barrier
	s_setprio 1
	v_mfma_f32_16x16x32_bf16 v[142:145], v[66:69], v[162:165], v[142:145]
	v_mfma_f32_16x16x32_bf16 v[134:137], v[86:89], v[162:165], v[134:137]
	v_mfma_f32_16x16x32_bf16 v[126:129], v[66:69], v[170:173], v[126:129]
	v_mfma_f32_16x16x32_bf16 v[122:125], v[86:89], v[170:173], v[122:125]
	v_mfma_f32_16x16x32_bf16 v[110:113], v[66:69], v[196:199], v[110:113]
	v_mfma_f32_16x16x32_bf16 v[102:105], v[86:89], v[196:199], v[102:105]
	v_mfma_f32_16x16x32_bf16 v[90:93], v[66:69], v[204:207], v[90:93]
	v_mfma_f32_16x16x32_bf16 v[82:85], v[86:89], v[204:207], v[82:85]
	v_mfma_f32_16x16x32_bf16 v[142:145], v[70:73], v[166:169], v[142:145]
	v_mfma_f32_16x16x32_bf16 v[134:137], v[106:109], v[166:169], v[134:137]
	v_mfma_f32_16x16x32_bf16 v[126:129], v[70:73], v[174:177], v[126:129]
	v_mfma_f32_16x16x32_bf16 v[122:125], v[106:109], v[174:177], v[122:125]
	v_mfma_f32_16x16x32_bf16 v[110:113], v[70:73], v[200:203], v[110:113]
	v_mfma_f32_16x16x32_bf16 v[102:105], v[106:109], v[200:203], v[102:105]
	v_mfma_f32_16x16x32_bf16 v[90:93], v[70:73], v[208:211], v[90:93]
	v_mfma_f32_16x16x32_bf16 v[82:85], v[106:109], v[208:211], v[82:85]
	v_mfma_f32_16x16x32_bf16 v[138:141], v[146:149], v[162:165], v[138:141]
	v_mfma_f32_16x16x32_bf16 v[130:133], v[154:157], v[162:165], v[130:133]
	v_mfma_f32_16x16x32_bf16 v[118:121], v[146:149], v[170:173], v[118:121]
	v_mfma_f32_16x16x32_bf16 v[114:117], v[154:157], v[170:173], v[114:117]
	v_mfma_f32_16x16x32_bf16 v[98:101], v[146:149], v[196:199], v[98:101]
	v_mfma_f32_16x16x32_bf16 v[94:97], v[154:157], v[196:199], v[94:97]
	v_mfma_f32_16x16x32_bf16 v[78:81], v[146:149], v[204:207], v[78:81]
	v_mfma_f32_16x16x32_bf16 v[74:77], v[154:157], v[204:207], v[74:77]
	v_mfma_f32_16x16x32_bf16 v[138:141], v[150:153], v[166:169], v[138:141]
	v_mfma_f32_16x16x32_bf16 v[130:133], v[158:161], v[166:169], v[130:133]
	v_mfma_f32_16x16x32_bf16 v[118:121], v[150:153], v[174:177], v[118:121]
	v_mfma_f32_16x16x32_bf16 v[114:117], v[158:161], v[174:177], v[114:117]
	v_mfma_f32_16x16x32_bf16 v[98:101], v[150:153], v[200:203], v[98:101]
	v_mfma_f32_16x16x32_bf16 v[94:97], v[158:161], v[200:203], v[94:97]
	v_mfma_f32_16x16x32_bf16 v[78:81], v[150:153], v[208:211], v[78:81]
	v_mfma_f32_16x16x32_bf16 v[74:77], v[158:161], v[208:211], v[74:77]
	s_setprio 0
	s_barrier
	s_add_i32 s37, s53, 0x18000
	s_mov_b32 m0, s37
	ds_read_b128 v[162:165], v221 offset:49152
	ds_read_b128 v[166:169], v221 offset:50176
	ds_read_b128 v[170:173], v221 offset:51200
	ds_read_b128 v[174:177], v221 offset:52224
	s_add_u32 s98, s10, 0x80
	s_addc_u32 s99, s11, 0
	global_load_lds_dwordx4 v184, s[98:99]
	s_add_i32 m0, s37, 0x2000
	s_add_u32 s10, s10, 0x40080
	s_addc_u32 s11, s11, 0
	s_add_i32 s37, s53, 0x1c000
	global_load_lds_dwordx4 v188, s[98:99]
	s_mov_b32 m0, s37
	ds_read_b128 v[196:199], v221 offset:53248
	global_load_lds_dwordx4 v184, s[10:11]
	s_add_i32 m0, s37, 0x2000
	ds_read_b128 v[200:203], v221 offset:54272
	global_load_lds_dwordx4 v188, s[10:11]
	s_add_u32 s98, s44, 0xfffc0080
	s_addc_u32 s99, s45, -1
	s_mov_b32 m0, s60
	ds_read_b128 v[204:207], v221 offset:55296
	global_load_lds_dwordx4 v182, s[98:99]
	s_mov_b32 m0, s61
	ds_read_b128 v[208:211], v221 offset:56320
	global_load_lds_dwordx4 v186, s[98:99]
	s_waitcnt vmcnt(8)
	s_waitcnt lgkmcnt(0)
	s_barrier
	s_setprio 1
	v_mfma_f32_16x16x32_bf16 v[62:65], v[66:69], v[162:165], v[62:65]
	v_mfma_f32_16x16x32_bf16 v[54:57], v[86:89], v[162:165], v[54:57]
	v_mfma_f32_16x16x32_bf16 v[46:49], v[66:69], v[170:173], v[46:49]
	v_mfma_f32_16x16x32_bf16 v[42:45], v[86:89], v[170:173], v[42:45]
	v_mfma_f32_16x16x32_bf16 v[30:33], v[66:69], v[196:199], v[30:33]
	v_mfma_f32_16x16x32_bf16 v[26:29], v[86:89], v[196:199], v[26:29]
	v_mfma_f32_16x16x32_bf16 v[14:17], v[66:69], v[204:207], v[14:17]
	v_mfma_f32_16x16x32_bf16 v[10:13], v[86:89], v[204:207], v[10:13]
	v_mfma_f32_16x16x32_bf16 v[62:65], v[70:73], v[166:169], v[62:65]
	v_mfma_f32_16x16x32_bf16 v[54:57], v[106:109], v[166:169], v[54:57]
	v_mfma_f32_16x16x32_bf16 v[46:49], v[70:73], v[174:177], v[46:49]
	v_mfma_f32_16x16x32_bf16 v[42:45], v[106:109], v[174:177], v[42:45]
	v_mfma_f32_16x16x32_bf16 v[30:33], v[70:73], v[200:203], v[30:33]
	v_mfma_f32_16x16x32_bf16 v[26:29], v[106:109], v[200:203], v[26:29]
	v_mfma_f32_16x16x32_bf16 v[14:17], v[70:73], v[208:211], v[14:17]
	v_mfma_f32_16x16x32_bf16 v[10:13], v[106:109], v[208:211], v[10:13]
	v_mfma_f32_16x16x32_bf16 v[58:61], v[146:149], v[162:165], v[58:61]
	v_mfma_f32_16x16x32_bf16 v[50:53], v[154:157], v[162:165], v[50:53]
	v_mfma_f32_16x16x32_bf16 v[38:41], v[146:149], v[170:173], v[38:41]
	v_mfma_f32_16x16x32_bf16 v[34:37], v[154:157], v[170:173], v[34:37]
	v_mfma_f32_16x16x32_bf16 v[22:25], v[146:149], v[196:199], v[22:25]
	v_mfma_f32_16x16x32_bf16 v[18:21], v[154:157], v[196:199], v[18:21]
	v_mfma_f32_16x16x32_bf16 v[6:9], v[146:149], v[204:207], v[6:9]
	v_mfma_f32_16x16x32_bf16 v[2:5], v[154:157], v[204:207], v[2:5]
	v_mfma_f32_16x16x32_bf16 v[58:61], v[150:153], v[166:169], v[58:61]
	v_mfma_f32_16x16x32_bf16 v[50:53], v[158:161], v[166:169], v[50:53]
	v_mfma_f32_16x16x32_bf16 v[38:41], v[150:153], v[174:177], v[38:41]
	v_mfma_f32_16x16x32_bf16 v[34:37], v[158:161], v[174:177], v[34:37]
	v_mfma_f32_16x16x32_bf16 v[22:25], v[150:153], v[200:203], v[22:25]
	v_mfma_f32_16x16x32_bf16 v[18:21], v[158:161], v[200:203], v[18:21]
	v_mfma_f32_16x16x32_bf16 v[6:9], v[150:153], v[208:211], v[6:9]
	v_mfma_f32_16x16x32_bf16 v[2:5], v[158:161], v[208:211], v[2:5]
	s_setprio 0
	s_barrier
	s_add_i32 s22, s22, 2
	s_add_u32 s8, s8, 0x100
	s_addc_u32 s9, s9, 0
	s_add_u32 s5, s5, 0x100
	s_addc_u32 s7, s7, 0
	s_cmp_gt_u32 s22, 13
	s_cbranch_scc0 .LBB0_991
